# stick-breaking tile loop rotated: next tile K fragments prefetched from LDS during the carry MFMA / liveness test
# speedup vs baseline: 1.0048x; 1.0048x over previous
; #define LAS __attribute__((address_space(3)))
; #define MFMA32(a, b, c) __builtin_amdgcn_mfma_f32_32x32x16_bf16((a), (b), (c), 0, 0, 0)
; __device__ __forceinline__ void sb_unit(int b, int h, int qb, const bf16* U, const bf16* VT, bf16* Y, unsigned char* lds, int wid, int lane, int& res_lo, int& res_hi) {
;     ...
;         asm volatile("s_waitcnt vmcnt(0)" ::: "memory");
;         __syncthreads();
; #pragma unroll 1
;         for (int t = (top < mytile ? top : mytile); t >= lo && alive; --t) {
;             const LAS unsigned char* Kb = kfp + (t & 7) * 16384; const LAS unsigned char* Vb = vfp + (t & 7) * 16384;
;             f32x16 y0 = f32x16{}, y1 = f32x16{};
; #pragma unroll
;             for (int ks = 0; ks < 4; ++ks) { const bf16x8 a0 = *(const LAS bf16x8*)(Kb + kofs[ks]), a1 = *(const LAS bf16x8*)(Kb + 4096 + kofs[ks]); y0 = MFMA32(a0, qf[ks], y0); y1 = MFMA32(a1, qf[ks], y1); }
; #pragma unroll
;             for (int r = 0; r < 16; ++r) { y0[r] = fminf(y0[r], 100.f); y1[r] = fminf(y1[r], 100.f); }
;             if (t == mytile) {
;                 int tqm = tq - 64 * t - 8 * hi; asm volatile("" : "+v"(tqm));
; #pragma unroll
;                 for (int r = 0; r < 16; ++r) { const int key = 16 * (r >> 3) + (r & 7); if (key >= tqm) y0[r] = -INFINITY; if (key + 32 >= tqm) y1[r] = -INFINITY; }
;             }
.LBB0_724:
	s_add_i32 s33, s6, 1
	s_cmp_gt_i32 s8, s6
	s_cselect_b32 s83, s33, s8
	s_min_i32 s89, s90, s88
	s_cmp_ge_i32 s89, s87
	s_waitcnt vmcnt(0)
	s_cselect_b64 s[6:7], -1, 0
	s_and_b64 s[6:7], s[6:7], s[2:3]
	s_andn2_b64 vcc, exec, s[6:7]
	s_waitcnt vmcnt(0) lgkmcnt(0)
	s_barrier
	s_cbranch_vccnz .LBB0_733
	s_min_i32 s2, s96, s90
	s_lshl_b32 s82, s2, 14
	s_and_b32 s69, s82, 0x1c000
	v_add_u32_e32 v0, s69, v154
	v_add_u32_e32 v6, v0, v146
	v_add_u32_e32 v10, v0, v148
	ds_read_b128 v[212:215], v6
	ds_read_b128 v[216:219], v6 offset:4096
	ds_read_b128 v[220:223], v10
	ds_read_b128 v[224:227], v10 offset:4096
	v_add_u32_e32 v10, v0, v150
	v_add_u32_e32 v0, v0, v152
	ds_read_b128 v[228:231], v10
	ds_read_b128 v[232:235], v10 offset:4096
	ds_read_b128 v[236:239], v0
	ds_read_b128 v[240:243], v0 offset:4096
.LBB0_726:
	s_and_b32 s69, s82, 0x1c000
	s_cmp_lg_u32 s96, s89
	s_waitcnt lgkmcnt(7)
	v_mfma_f32_32x32x16_bf16 v[64:79], v[212:215], v[100:103], 0
	s_waitcnt lgkmcnt(6)
	v_mfma_f32_32x32x16_bf16 v[80:95], v[216:219], v[100:103], 0
	s_waitcnt lgkmcnt(5)
	v_mfma_f32_32x32x16_bf16 v[64:79], v[220:223], v[104:107], v[64:79]
	s_waitcnt lgkmcnt(4)
	v_mfma_f32_32x32x16_bf16 v[80:95], v[224:227], v[104:107], v[80:95]
	s_waitcnt lgkmcnt(3)
	v_mfma_f32_32x32x16_bf16 v[64:79], v[228:231], v[108:111], v[64:79]
	s_waitcnt lgkmcnt(2)
	v_mfma_f32_32x32x16_bf16 v[80:95], v[232:235], v[108:111], v[80:95]
	s_waitcnt lgkmcnt(1)
	v_mfma_f32_32x32x16_bf16 v[64:79], v[236:239], v[112:115], v[64:79]
	s_waitcnt lgkmcnt(0)
	v_mfma_f32_32x32x16_bf16 v[80:95], v[240:243], v[112:115], v[80:95]
	s_nop 9
	v_min_f32_e32 v0, 0x42c80000, v64
	v_min_f32_e32 v3, 0x42c80000, v65
	v_min_f32_e32 v4, 0x42c80000, v66
	v_min_f32_e32 v7, 0x42c80000, v67
	v_min_f32_e32 v9, 0x42c80000, v68
	v_min_f32_e32 v12, 0x42c80000, v69
	v_min_f32_e32 v13, 0x42c80000, v70
	v_min_f32_e32 v15, 0x42c80000, v71
	v_min_f32_e32 v157, 0x42c80000, v73
	v_min_f32_e32 v159, 0x42c80000, v74
	v_min_f32_e32 v161, 0x42c80000, v75
	v_min_f32_e32 v164, 0x42c80000, v76
	v_min_f32_e32 v165, 0x42c80000, v77
	v_min_f32_e32 v167, 0x42c80000, v78
	v_min_f32_e32 v169, 0x42c80000, v79
	v_min_f32_e32 v2, 0x42c80000, v80
	v_min_f32_e32 v5, 0x42c80000, v81
	v_min_f32_e32 v81, 0x42c80000, v72
	v_min_f32_e32 v6, 0x42c80000, v82
	v_min_f32_e32 v8, 0x42c80000, v83
	v_min_f32_e32 v10, 0x42c80000, v84
	v_min_f32_e32 v11, 0x42c80000, v85
	v_min_f32_e32 v14, 0x42c80000, v86
	v_min_f32_e32 v80, 0x42c80000, v87
	v_min_f32_e32 v82, 0x42c80000, v88
	v_min_f32_e32 v158, 0x42c80000, v89
	v_min_f32_e32 v160, 0x42c80000, v90
	v_min_f32_e32 v162, 0x42c80000, v91
	v_min_f32_e32 v163, 0x42c80000, v92
	v_min_f32_e32 v166, 0x42c80000, v93
	v_min_f32_e32 v168, 0x42c80000, v94
	v_min_f32_e32 v170, 0x42c80000, v95
	s_cbranch_scc1 .LBB0_728
	v_mov_b32_e32 v64, v156
	s_nop 0
	v_cmp_lt_i32_e64 s[60:61], 22, v64
	v_cmp_lt_i32_e64 s[64:65], 23, v64
	v_cmp_lt_i32_e64 s[58:59], 21, v64
	s_or_b64 s[60:61], s[64:65], s[60:61]
	v_cmp_lt_i32_e64 s[56:57], 20, v64
	s_or_b64 s[58:59], s[60:61], s[58:59]
	v_cmp_lt_i32_e64 s[54:55], 19, v64
	s_or_b64 s[56:57], s[58:59], s[56:57]
	v_cmp_lt_i32_e64 s[52:53], 18, v64
	s_or_b64 s[54:55], s[56:57], s[54:55]
	v_cmp_lt_i32_e64 s[50:51], 17, v64
	s_or_b64 s[52:53], s[54:55], s[52:53]
	v_cmp_lt_i32_e64 s[48:49], 16, v64
	s_or_b64 s[50:51], s[52:53], s[50:51]
	v_cmp_lt_i32_e64 s[46:47], 7, v64
	s_or_b64 s[48:49], s[50:51], s[48:49]
	v_cmp_lt_i32_e64 s[44:45], 6, v64
	s_or_b64 s[46:47], s[48:49], s[46:47]
	v_cmp_lt_i32_e64 s[42:43], 5, v64
	s_or_b64 s[44:45], s[46:47], s[44:45]
	v_cmp_lt_i32_e64 s[40:41], 4, v64
	s_or_b64 s[42:43], s[44:45], s[42:43]
	v_cmp_lt_i32_e64 s[38:39], 3, v64
	s_or_b64 s[40:41], s[42:43], s[40:41]
	v_cmp_lt_i32_e64 s[36:37], 2, v64
	s_or_b64 s[38:39], s[40:41], s[38:39]
	v_cmp_lt_i32_e64 s[34:35], 1, v64
	s_or_b64 s[36:37], s[38:39], s[36:37]
	v_cmp_lt_i32_e64 s[30:31], 0, v64
	s_or_b64 s[34:35], s[36:37], s[34:35]
	s_or_b64 s[30:31], s[34:35], s[30:31]
	v_cmp_lt_i32_e64 s[62:63], 54, v64
	v_cndmask_b32_e64 v0, v145, v0, s[30:31]
	v_cmp_lt_i32_e64 s[30:31], 55, v64
	v_cmp_lt_i32_e64 s[28:29], 53, v64
	v_cmp_lt_i32_e64 s[26:27], 52, v64
	v_cndmask_b32_e64 v170, v145, v170, s[30:31]
	s_or_b64 s[30:31], s[30:31], s[62:63]
	s_or_b64 s[28:29], s[30:31], s[28:29]
	v_cmp_lt_i32_e64 s[24:25], 51, v64
	s_or_b64 s[26:27], s[28:29], s[26:27]
	v_cmp_lt_i32_e64 s[22:23], 50, v64
	s_or_b64 s[24:25], s[26:27], s[24:25]
	v_cmp_lt_i32_e64 s[20:21], 49, v64
	s_or_b64 s[22:23], s[24:25], s[22:23]
	v_cmp_lt_i32_e64 s[18:19], 48, v64
	s_or_b64 s[20:21], s[22:23], s[20:21]
	v_cmp_lt_i32_e64 s[16:17], 39, v64
	s_or_b64 s[18:19], s[20:21], s[18:19]
	v_cmp_lt_i32_e64 s[14:15], 38, v64
	s_or_b64 s[16:17], s[18:19], s[16:17]
	v_cmp_lt_i32_e64 s[12:13], 37, v64
	s_or_b64 s[14:15], s[16:17], s[14:15]
	v_cmp_lt_i32_e64 s[10:11], 36, v64
	s_or_b64 s[12:13], s[14:15], s[12:13]
	v_cmp_lt_i32_e64 s[8:9], 35, v64
	s_or_b64 s[10:11], s[12:13], s[10:11]
	v_cmp_lt_i32_e64 s[6:7], 34, v64
	s_or_b64 s[8:9], s[10:11], s[8:9]
	v_cmp_lt_i32_e64 s[2:3], 33, v64
	s_or_b64 s[6:7], s[8:9], s[6:7]
	v_cmp_lt_i32_e32 vcc, 32, v64
	s_or_b64 s[2:3], s[6:7], s[2:3]
	s_or_b64 vcc, s[2:3], vcc
	v_cndmask_b32_e64 v169, v145, v169, s[64:65]
	v_cndmask_b32_e64 v167, v145, v167, s[60:61]
	v_cndmask_b32_e64 v165, v145, v165, s[58:59]
	v_cndmask_b32_e64 v164, v145, v164, s[56:57]
	v_cndmask_b32_e64 v161, v145, v161, s[54:55]
	v_cndmask_b32_e64 v159, v145, v159, s[52:53]
	v_cndmask_b32_e64 v157, v145, v157, s[50:51]
	v_cndmask_b32_e64 v81, v145, v81, s[48:49]
	v_cndmask_b32_e64 v15, v145, v15, s[46:47]
	v_cndmask_b32_e64 v13, v145, v13, s[44:45]
	v_cndmask_b32_e64 v12, v145, v12, s[42:43]
	v_cndmask_b32_e64 v9, v145, v9, s[40:41]
	v_cndmask_b32_e64 v7, v145, v7, s[38:39]
	v_cndmask_b32_e64 v4, v145, v4, s[36:37]
	v_cndmask_b32_e64 v3, v145, v3, s[34:35]
	v_cndmask_b32_e64 v168, v145, v168, s[30:31]
	v_cndmask_b32_e64 v166, v145, v166, s[28:29]
	v_cndmask_b32_e64 v163, v145, v163, s[26:27]
	v_cndmask_b32_e64 v162, v145, v162, s[24:25]
	v_cndmask_b32_e64 v160, v145, v160, s[22:23]
	v_cndmask_b32_e64 v158, v145, v158, s[20:21]
	v_cndmask_b32_e64 v82, v145, v82, s[18:19]
	v_cndmask_b32_e64 v80, v145, v80, s[16:17]
	v_cndmask_b32_e64 v14, v145, v14, s[14:15]
	v_cndmask_b32_e64 v11, v145, v11, s[12:13]
	v_cndmask_b32_e64 v10, v145, v10, s[10:11]
	v_cndmask_b32_e64 v8, v145, v8, s[8:9]
	v_cndmask_b32_e64 v6, v145, v6, s[6:7]
	v_cndmask_b32_e64 v5, v145, v5, s[2:3]
	v_cndmask_b32_e32 v2, v145, v2, vcc
; #define LAS __attribute__((address_space(3)))
; #define MFMA32(a, b, c) __builtin_amdgcn_mfma_f32_32x32x16_bf16((a), (b), (c), 0, 0, 0)
; __device__ __forceinline__ void sb_unit(int b, int h, int qb, const bf16* U, const bf16* VT, bf16* Y, unsigned char* lds, int wid, int lane, int& res_lo, int& res_hi) {
;     ...
;             f32x16 l0, l1;
; #pragma unroll
;             for (int r = 0; r < 16; ++r) { l0[r] = __builtin_amdgcn_logf(1.f + __builtin_amdgcn_exp2f(y0[r])); l1[r] = __builtin_amdgcn_logf(1.f + __builtin_amdgcn_exp2f(y1[r])); }
;             bf16x8 lb[4]; lb[0] = pack8(l0, 0); lb[1] = pack8(l0, 8); lb[2] = pack8(l1, 0); lb[3] = pack8(l1, 8);
; #pragma unroll
;             for (int r = 0; r < 16; ++r) { y0[r] -= l0[r]; y1[r] -= l1[r]; }
;             f32x16 X = MFMA32(JN, lb[2], C); X = MFMA32(JN, lb[3], X);
;             f32x16 f1 = MFMA32(TM[0], lb[2], C); f1 = MFMA32(TM[1], lb[3], f1);
;             f32x16 f0 = MFMA32(TM[0], lb[0], X); f0 = MFMA32(TM[1], lb[1], f0);
;             C = MFMA32(JN, lb[0], X); C = MFMA32(JN, lb[1], C);
; #pragma unroll
;             for (int r = 0; r < 16; ++r) { y0[r] = __builtin_amdgcn_exp2f(y0[r] + f0[r]); y1[r] = __builtin_amdgcn_exp2f(y1[r] + f1[r]); }
;             bf16x8 pk[4]; pk[0] = pack8(y0, 0); pk[1] = pack8(y0, 8); pk[2] = pack8(y1, 0); pk[3] = pack8(y1, 8);
; #pragma unroll
;             for (int db = 0; db < 2; ++db)
; #pragma unroll
;                 for (int kk = 0; kk < 4; ++kk) { const bf16x8 vf = *(const LAS bf16x8*)(Vb + db * 4096 + vofs[kk]); o[db] = MFMA32(vf, pk[kk], o[db]); }
.LBB0_728:
	v_exp_f32_e32 v64, v0
	v_exp_f32_e32 v65, v2
	v_exp_f32_e32 v66, v3
	s_mov_b32 s70, s68
	v_add_f32_e32 v64, 1.0, v64
	v_log_f32_e32 v83, v64
	v_add_f32_e32 v64, 1.0, v65
	v_log_f32_e32 v92, v64
	v_exp_f32_e32 v64, v5
	v_add_f32_e32 v65, 1.0, v66
	v_log_f32_e32 v93, v65
	v_exp_f32_e32 v65, v4
	v_add_f32_e32 v64, 1.0, v64
	v_log_f32_e32 v94, v64
	v_exp_f32_e32 v64, v6
	v_add_f32_e32 v65, 1.0, v65
	v_log_f32_e32 v95, v65
	v_exp_f32_e32 v65, v7
	v_add_f32_e32 v64, 1.0, v64
	v_log_f32_e32 v184, v64
	v_exp_f32_e32 v64, v8
	v_add_f32_e32 v65, 1.0, v65
	v_log_f32_e32 v185, v65
	v_exp_f32_e32 v65, v9
	v_add_f32_e32 v64, 1.0, v64
	v_log_f32_e32 v186, v64
	v_exp_f32_e32 v64, v10
	v_add_f32_e32 v65, 1.0, v65
	v_log_f32_e32 v187, v65
	v_exp_f32_e32 v65, v12
	v_add_f32_e32 v64, 1.0, v64
	v_log_f32_e32 v188, v64
	v_exp_f32_e32 v64, v11
	v_add_f32_e32 v65, 1.0, v65
	v_log_f32_e32 v189, v65
	v_exp_f32_e32 v65, v13
	v_add_f32_e32 v64, 1.0, v64
	v_log_f32_e32 v190, v64
	v_exp_f32_e32 v64, v14
	v_add_f32_e32 v65, 1.0, v65
	v_log_f32_e32 v191, v65
	v_exp_f32_e32 v65, v15
	v_add_f32_e32 v64, 1.0, v64
	v_log_f32_e32 v192, v64
	v_exp_f32_e32 v64, v80
	v_add_f32_e32 v65, 1.0, v65
	v_log_f32_e32 v193, v65
	v_exp_f32_e32 v65, v81
	v_add_f32_e32 v64, 1.0, v64
	v_log_f32_e32 v194, v64
	v_exp_f32_e32 v64, v82
	v_add_f32_e32 v65, 1.0, v65
	v_log_f32_e32 v195, v65
	v_exp_f32_e32 v65, v157
	v_add_f32_e32 v64, 1.0, v64
	v_log_f32_e32 v196, v64
	v_exp_f32_e32 v64, v158
	v_add_f32_e32 v65, 1.0, v65
	v_log_f32_e32 v197, v65
	v_exp_f32_e32 v65, v159
	v_add_f32_e32 v64, 1.0, v64
	v_log_f32_e32 v198, v64
	v_exp_f32_e32 v64, v160
	v_add_f32_e32 v65, 1.0, v65
	v_log_f32_e32 v199, v65
	v_exp_f32_e32 v65, v161
	v_add_f32_e32 v64, 1.0, v64
	v_log_f32_e32 v200, v64
	v_exp_f32_e32 v64, v162
	v_add_f32_e32 v65, 1.0, v65
	v_log_f32_e32 v201, v65
	v_exp_f32_e32 v65, v164
	v_add_f32_e32 v64, 1.0, v64
	v_log_f32_e32 v202, v64
	v_exp_f32_e32 v64, v163
	v_add_f32_e32 v65, 1.0, v65
	v_log_f32_e32 v203, v65
	v_exp_f32_e32 v65, v165
	v_add_f32_e32 v64, 1.0, v64
	v_log_f32_e32 v204, v64
	v_exp_f32_e32 v64, v166
	v_add_f32_e32 v65, 1.0, v65
	v_log_f32_e32 v205, v65
	v_exp_f32_e32 v65, v167
	v_add_f32_e32 v64, 1.0, v64
	v_log_f32_e32 v206, v64
	v_exp_f32_e32 v64, v168
	v_add_f32_e32 v65, 1.0, v65
	s_mov_b32 s71, s68
	v_add_u32_e32 v171, s69, v155
	v_log_f32_e32 v207, v65
	v_exp_f32_e32 v65, v169
	s_mov_b32 s69, s68
	v_mov_b64_e32 v[178:179], s[70:71]
	v_exp_f32_e32 v66, v170
	v_mov_b64_e32 v[176:177], s[68:69]
	v_add_f32_e32 v64, 1.0, v64
	v_log_f32_e32 v208, v64
	v_add_f32_e32 v64, 1.0, v65
	v_log_f32_e32 v209, v64
	v_add_f32_e32 v64, 1.0, v66
	v_cvt_pk_bf16_f32 v84, v92, v94
	v_cvt_pk_bf16_f32 v85, v184, v186
	v_cvt_pk_bf16_f32 v86, v188, v190
	v_cvt_pk_bf16_f32 v87, v192, v194
	v_log_f32_e32 v210, v64
	v_cvt_pk_bf16_f32 v88, v196, v198
	v_mfma_f32_32x32x16_bf16 v[64:79], v[176:179], v[84:87], v[48:63]
	v_cvt_pk_bf16_f32 v89, v200, v202
	v_cvt_pk_bf16_f32 v90, v204, v206
	v_cvt_pk_bf16_f32 v91, v208, v210
	v_cvt_pk_bf16_f32 v172, v83, v93
	v_cvt_pk_bf16_f32 v173, v95, v185
	v_cvt_pk_bf16_f32 v174, v187, v189
	v_cvt_pk_bf16_f32 v175, v191, v193
	v_mfma_f32_32x32x16_bf16 v[64:79], v[176:179], v[88:91], v[64:79]
	v_sub_f32_e32 v0, v0, v83
	v_sub_f32_e32 v2, v2, v92
	v_sub_f32_e32 v3, v3, v93
	v_sub_f32_e32 v5, v5, v94
	v_sub_f32_e32 v4, v4, v95
	v_sub_f32_e32 v6, v6, v184
	v_sub_f32_e32 v7, v7, v185
	v_mfma_f32_32x32x16_bf16 v[48:63], v[96:99], v[84:87], v[48:63]
	v_sub_f32_e32 v8, v8, v186
	v_sub_f32_e32 v184, v80, v194
	v_sub_f32_e32 v185, v81, v195
	v_sub_f32_e32 v186, v82, v196
	v_cvt_pk_bf16_f32 v180, v195, v197
	v_cvt_pk_bf16_f32 v181, v199, v201
	v_cvt_pk_bf16_f32 v182, v203, v205
	v_mfma_f32_32x32x16_bf16 v[48:63], v[116:119], v[88:91], v[48:63]
	v_cvt_pk_bf16_f32 v183, v207, v209
	v_sub_f32_e32 v9, v9, v187
	v_sub_f32_e32 v10, v10, v188
	v_sub_f32_e32 v12, v12, v189
	v_sub_f32_e32 v11, v11, v190
	v_sub_f32_e32 v13, v13, v191
	v_sub_f32_e32 v14, v14, v192
	v_mfma_f32_32x32x16_bf16 v[80:95], v[96:99], v[172:175], v[64:79]
	s_nop 3
	v_add_f32_e32 v2, v2, v48
	v_sub_f32_e32 v15, v15, v193
	v_sub_f32_e32 v157, v157, v197
	v_sub_f32_e32 v158, v158, v198
	v_sub_f32_e32 v159, v159, v199
	v_sub_f32_e32 v160, v160, v200
	v_sub_f32_e32 v161, v161, v201
	v_mfma_f32_32x32x16_bf16 v[80:95], v[116:119], v[180:183], v[80:95]
	v_sub_f32_e32 v162, v162, v202
	v_sub_f32_e32 v164, v164, v203
	v_sub_f32_e32 v163, v163, v204
	v_sub_f32_e32 v165, v165, v205
	v_sub_f32_e32 v166, v166, v206
	v_sub_f32_e32 v167, v167, v207
	v_sub_f32_e32 v168, v168, v208
	s_nop 4
	v_add_f32_e32 v0, v0, v80
	v_exp_f32_e32 v80, v2
	v_add_f32_e32 v2, v3, v81
	v_exp_f32_e32 v48, v2
	v_add_f32_e32 v2, v5, v49
	v_exp_f32_e32 v81, v2
	v_add_f32_e32 v2, v4, v82
	v_exp_f32_e32 v49, v2
	v_add_f32_e32 v2, v6, v50
	v_exp_f32_e32 v82, v2
	v_add_f32_e32 v2, v7, v83
	v_exp_f32_e32 v7, v2
	v_add_f32_e32 v2, v8, v51
	v_exp_f32_e32 v83, v2
	v_add_f32_e32 v2, v9, v84
	v_exp_f32_e32 v8, v2
	v_add_f32_e32 v2, v10, v52
	v_exp_f32_e32 v84, v2
	v_add_f32_e32 v2, v12, v85
	v_exp_f32_e32 v9, v2
	v_add_f32_e32 v2, v11, v53
	v_exp_f32_e32 v85, v2
	v_add_f32_e32 v2, v13, v86
	v_exp_f32_e32 v10, v2
	v_add_f32_e32 v2, v14, v54
	v_exp_f32_e32 v14, v2
	v_add_f32_e32 v2, v15, v87
	v_exp_f32_e32 v11, v2
	v_add_f32_e32 v2, v184, v55
	v_exp_f32_e32 v15, v2
	v_add_f32_e32 v2, v185, v88
	v_exp_f32_e32 v52, v2
	v_add_f32_e32 v2, v186, v56
	v_exp_f32_e32 v88, v2
	v_add_f32_e32 v2, v157, v89
	v_exp_f32_e32 v53, v2
	v_add_f32_e32 v2, v158, v57
	v_exp_f32_e32 v89, v2
	v_add_f32_e32 v2, v159, v90
	v_exp_f32_e32 v54, v2
	v_add_f32_e32 v2, v160, v58
	v_exp_f32_e32 v90, v2
	v_add_f32_e32 v2, v161, v91
	v_exp_f32_e32 v55, v2
	v_add_f32_e32 v2, v162, v59
	v_exp_f32_e32 v91, v2
	v_add_f32_e32 v2, v164, v92
	v_exp_f32_e32 v56, v2
	v_add_f32_e32 v2, v163, v60
	v_exp_f32_e32 v60, v2
	v_add_f32_e32 v2, v165, v93
	v_exp_f32_e32 v57, v2
	v_add_f32_e32 v2, v166, v61
	v_exp_f32_e32 v61, v2
	v_add_f32_e32 v2, v167, v94
	v_exp_f32_e32 v58, v2
	v_add_f32_e32 v2, v168, v62
	v_add_u32_e32 v50, v171, v147
	v_exp_f32_e32 v0, v0
	v_exp_f32_e32 v62, v2
	ds_read_b128 v[2:5], v50 offset:8192
	v_sub_f32_e32 v169, v169, v209
	v_add_f32_e32 v6, v169, v95
	v_exp_f32_e32 v59, v6
	v_cvt_pk_bf16_f32 v6, v0, v48
	v_add_u32_e32 v0, v171, v149
	v_cvt_pk_bf16_f32 v7, v49, v7
	v_cvt_pk_bf16_f32 v8, v8, v9
	v_cvt_pk_bf16_f32 v9, v10, v11
	ds_read_b128 v[10:13], v0 offset:8192
	ds_read_b128 v[48:51], v50 offset:12288
	s_waitcnt lgkmcnt(2)
; #define LAS __attribute__((address_space(3)))
; #define MFMA32(a, b, c) __builtin_amdgcn_mfma_f32_32x32x16_bf16((a), (b), (c), 0, 0, 0)
; __device__ __forceinline__ void sb_unit(int b, int h, int qb, const bf16* U, const bf16* VT, bf16* Y, unsigned char* lds, int wid, int lane, int& res_lo, int& res_hi) {
;     ...
;             f32x16 f0 = MFMA32(TM[0], lb[0], X); f0 = MFMA32(TM[1], lb[1], f0);
;             C = MFMA32(JN, lb[0], X); C = MFMA32(JN, lb[1], C);
; #pragma unroll
;             for (int r = 0; r < 16; ++r) { y0[r] = __builtin_amdgcn_exp2f(y0[r] + f0[r]); y1[r] = __builtin_amdgcn_exp2f(y1[r] + f1[r]); }
;             bf16x8 pk[4]; pk[0] = pack8(y0, 0); pk[1] = pack8(y0, 8); pk[2] = pack8(y1, 0); pk[3] = pack8(y1, 8);
; #pragma unroll
;             for (int db = 0; db < 2; ++db)
; #pragma unroll
;                 for (int kk = 0; kk < 4; ++kk) { const bf16x8 vf = *(const LAS bf16x8*)(Vb + db * 4096 + vofs[kk]); o[db] = MFMA32(vf, pk[kk], o[db]); }
;             alive = __any(C[0] > -160.f);
	v_mfma_f32_32x32x16_bf16 v[32:47], v[2:5], v[6:9], v[32:47]
	v_add_u32_e32 v86, v171, v151
	v_cvt_pk_bf16_f32 v2, v52, v53
	v_cvt_pk_bf16_f32 v3, v54, v55
	v_cvt_pk_bf16_f32 v4, v56, v57
	v_cvt_pk_bf16_f32 v5, v58, v59
	ds_read_b128 v[52:55], v86 offset:8192
	ds_read_b128 v[56:59], v0 offset:12288
	v_sub_f32_e32 v170, v170, v210
	s_waitcnt lgkmcnt(2)
	v_mfma_f32_32x32x16_bf16 v[16:31], v[48:51], v[6:9], v[16:31]
	v_add_u32_e32 v0, v171, v153
	s_mov_b32 s2, 0xc3200000
	v_mfma_f32_32x32x16_bf16 v[32:47], v[10:13], v[2:5], v[32:47]
	v_cvt_pk_bf16_f32 v13, v14, v15
	v_add_f32_e32 v14, v170, v63
	v_cvt_pk_bf16_f32 v10, v80, v81
	v_cvt_pk_bf16_f32 v11, v82, v83
	v_cvt_pk_bf16_f32 v12, v84, v85
	ds_read_b128 v[80:83], v0 offset:8192
	ds_read_b128 v[84:87], v86 offset:12288
	v_exp_f32_e32 v14, v14
	s_waitcnt lgkmcnt(2)
	v_mfma_f32_32x32x16_bf16 v[16:31], v[56:59], v[2:5], v[16:31]
	v_mfma_f32_32x32x16_bf16 v[32:47], v[52:55], v[10:13], v[32:47]
	v_cvt_pk_bf16_f32 v54, v60, v61
	v_cvt_pk_bf16_f32 v55, v62, v14
	ds_read_b128 v[60:63], v0 offset:12288
	v_cvt_pk_bf16_f32 v52, v88, v89
	v_cvt_pk_bf16_f32 v53, v90, v91
	v_mfma_f32_32x32x16_bf16 v[64:79], v[176:179], v[172:175], v[64:79]
	s_waitcnt lgkmcnt(1)
	v_mfma_f32_32x32x16_bf16 v[16:31], v[84:87], v[10:13], v[16:31]
	v_mfma_f32_32x32x16_bf16 v[32:47], v[80:83], v[52:55], v[32:47]
	s_waitcnt lgkmcnt(0)
	v_mfma_f32_32x32x16_bf16 v[16:31], v[60:63], v[52:55], v[16:31]
	v_mfma_f32_32x32x16_bf16 v[48:63], v[176:179], v[180:183], v[64:79]
	s_add_i32 s70, s82, 0xffffc000
	s_and_b32 s70, s70, 0x1c000
	v_add_u32_e32 v0, s70, v154
	v_add_u32_e32 v6, v0, v146
	v_add_u32_e32 v10, v0, v148
	ds_read_b128 v[212:215], v6
	ds_read_b128 v[216:219], v6 offset:4096
	ds_read_b128 v[220:223], v10
	ds_read_b128 v[224:227], v10 offset:4096
	v_add_u32_e32 v10, v0, v150
	v_add_u32_e32 v0, v0, v152
	ds_read_b128 v[228:231], v10
	ds_read_b128 v[232:235], v10 offset:4096
	ds_read_b128 v[236:239], v0
	ds_read_b128 v[240:243], v0 offset:4096
	v_cmp_lt_f32_e32 vcc, s2, v48
	s_cmp_lg_u64 vcc, 0
	s_cselect_b64 s[2:3], -1, 0
	s_add_i32 s6, s89, -1
	s_cmp_gt_i32 s89, s87
	s_cselect_b64 s[8:9], -1, 0
	s_and_b64 s[8:9], s[8:9], s[2:3]
	s_andn2_b64 vcc, exec, s[8:9]
	s_addk_i32 s82, 0xc000
	s_cbranch_vccnz .LBB0_733
	s_mov_b32 s89, s6
	s_branch .LBB0_726
